# flattened grid barrier + the middle local arriver of each round starts an early L2 write-back (hint)
# baseline (speedup 1.0000x reference)
.LBB0_860:
	v_readlane_b32 s0, v252, 10
	s_lshl_b32 s50, s0, 2
	v_lshl_add_u64 v[4:5], v[2:3], 0, s[50:51]
	v_add_co_u32_e32 v10, vcc, 0x1000, v4
	v_cvt_f32_u32_e32 v1, v8
	s_nop 0
	v_addc_co_u32_e32 v11, vcc, 0, v5, vcc
	flat_atomic_add v7, v[10:11], v223 offset:1024 sc0
	v_rcp_iflag_f32_e32 v1, v1
	v_sub_u32_e32 v9, 0, v8
	v_mul_f32_e32 v1, 0x4f7ffffe, v1
	v_cvt_u32_f32_e32 v1, v1
	v_mul_lo_u32 v9, v9, v1
	v_mul_hi_u32 v9, v1, v9
	v_add_u32_e32 v1, v1, v9
	s_waitcnt vmcnt(0) lgkmcnt(0)
	v_mul_hi_u32 v1, v7, v1
	v_mul_lo_u32 v9, v1, v8
	v_sub_u32_e32 v9, v7, v9
	v_cmp_ge_u32_e32 vcc, v9, v8
	v_add_u32_e32 v10, 1, v1
	v_add_u32_e32 v7, 1, v7
	v_cndmask_b32_e32 v1, v1, v10, vcc
	v_sub_u32_e32 v10, v9, v8
	v_cndmask_b32_e32 v9, v9, v10, vcc
	v_cmp_ge_u32_e32 vcc, v9, v8
	v_add_u32_e32 v9, 1, v1
	s_nop 0
	v_cndmask_b32_e32 v1, v1, v9, vcc
	v_mul_lo_u32 v12, v1, v8
	v_sub_u32_e32 v12, v7, v12
	v_lshlrev_b32_e32 v13, 1, v12
	v_sub_u32_e32 v13, v13, v8
	v_mad_u64_u32 v[8:9], s[0:1], v8, v1, v[8:9]
	s_mov_b64 s[26:27], 0x3000
	v_add_u32_e32 v9, 1, v1
	v_lshl_add_u64 v[10:11], v[2:3], 0, s[26:27]
	v_mul_lo_u32 v9, v9, v6
	v_cmp_ne_u32_e32 vcc, v7, v8
	s_cbranch_vccnz .Lgb_arrived
	buffer_wbl2 sc1
	buffer_inv sc1
	s_waitcnt vmcnt(0)
	flat_atomic_add v[10:11], v223 offset:1024
	s_branch .Lgb_poll
.Lgb_arrived:
	v_cmp_gt_u32_e32 vcc, 2, v13
	s_cbranch_vccz .Lgb_nohint
	buffer_wbl2 sc1
